# phase A norm loop: bf16 row prefetch made asynchronous with deferred bf16->f32 conversion (as in norm2), on top of v63
# speedup vs baseline: 1.0008x; 1.0008x over previous
.LBB0_324:
	s_and_b64 vcc, exec, s[12:13]
	s_mov_b32 s25, s24
	s_cmp_eq_u32 s100, 0
	s_cbranch_scc1 .Lmy_nA_copyA
	s_cmp_eq_u32 s101, 0
	s_cbranch_scc1 .Lmy_nA_waitA4
	s_waitcnt vmcnt(12)
	s_branch .Lmy_nA_convA

.Lmy_nA_convA:
	v_lshlrev_b32_e32 v28, 16, v50
	v_and_b32_e32 v29, 0xffff0000, v50
	v_lshlrev_b32_e32 v30, 16, v51
	v_and_b32_e32 v31, 0xffff0000, v51
	v_lshlrev_b32_e32 v24, 16, v52
	v_and_b32_e32 v25, 0xffff0000, v52
	v_lshlrev_b32_e32 v26, 16, v53
	v_and_b32_e32 v27, 0xffff0000, v53
	v_lshlrev_b32_e32 v20, 16, v54
	v_and_b32_e32 v21, 0xffff0000, v54
	v_lshlrev_b32_e32 v22, 16, v55
	v_and_b32_e32 v23, 0xffff0000, v55
	v_lshlrev_b32_e32 v16, 16, v56
	v_and_b32_e32 v17, 0xffff0000, v56
	v_lshlrev_b32_e32 v18, 16, v57
	v_and_b32_e32 v19, 0xffff0000, v57
	s_branch .Lmy_nA_doB
.Lmy_nA_copyA:
	s_waitcnt vmcnt(7)
	v_mov_b32_e32 v28, v60
	v_mov_b32_e32 v29, v61
	v_mov_b32_e32 v30, v62
	v_mov_b32_e32 v31, v63
	s_waitcnt vmcnt(6)
	v_mov_b32_e32 v24, v56
	v_mov_b32_e32 v25, v57
	v_mov_b32_e32 v26, v58
	v_mov_b32_e32 v27, v59
	s_waitcnt vmcnt(5)
	v_mov_b32_e32 v20, v52
	v_mov_b32_e32 v21, v53
	v_mov_b32_e32 v22, v54
	v_mov_b32_e32 v23, v55
	s_waitcnt vmcnt(4)
	v_mov_b32_e32 v16, v48
	v_mov_b32_e32 v17, v49
	v_mov_b32_e32 v18, v50
	v_mov_b32_e32 v19, v51
.Lmy_nA_doB:
	s_cmp_eq_u32 s101, 0
	s_cbranch_scc1 .Lmy_nA_copyB
	s_waitcnt vmcnt(4)
	v_lshlrev_b32_e32 v0, 16, v68
	v_and_b32_e32 v1, 0xffff0000, v68
	v_lshlrev_b32_e32 v2, 16, v69
	v_and_b32_e32 v3, 0xffff0000, v69
	v_lshlrev_b32_e32 v12, 16, v70
	v_and_b32_e32 v13, 0xffff0000, v70
	v_lshlrev_b32_e32 v14, 16, v71
	v_and_b32_e32 v15, 0xffff0000, v71
	v_lshlrev_b32_e32 v8, 16, v72
	v_and_b32_e32 v9, 0xffff0000, v72
	v_lshlrev_b32_e32 v10, 16, v73
	v_and_b32_e32 v11, 0xffff0000, v73
	v_lshlrev_b32_e32 v4, 16, v74
	v_and_b32_e32 v5, 0xffff0000, v74
	v_lshlrev_b32_e32 v6, 16, v75
	v_and_b32_e32 v7, 0xffff0000, v75
	s_branch .Lmy_nA_bottom
.Lmy_nA_copyB:
	s_waitcnt vmcnt(4)
	v_mov_b32_e32 v0, v78
	v_mov_b32_e32 v1, v79
	v_mov_b32_e32 v2, v80
	v_mov_b32_e32 v3, v81
	v_mov_b32_e32 v12, v74
	v_mov_b32_e32 v13, v75
	v_mov_b32_e32 v14, v76
	v_mov_b32_e32 v15, v77
	v_mov_b32_e32 v8, v70
	v_mov_b32_e32 v9, v71
	v_mov_b32_e32 v10, v72
	v_mov_b32_e32 v11, v73
	v_mov_b32_e32 v4, v66
	v_mov_b32_e32 v5, v67
	v_mov_b32_e32 v6, v68
	v_mov_b32_e32 v7, v69
.Lmy_nA_bottom:
	s_cbranch_vccnz .LBB0_402
.LBB0_325:
	s_mov_b32 s100, 0
	s_mov_b32 s101, 0
	v_cndmask_b32_e64 v48, 0, 1, s[8:9]
	v_cmp_ne_u32_e64 s[2:3], 1, v48
	s_andn2_b64 vcc, exec, s[8:9]
	s_mov_b64 s[10:11], -1
	s_cbranch_vccnz .LBB0_327
	v_readlane_b32 s10, v254, 14
	s_mul_i32 s10, s25, s10
	s_add_i32 s12, s10, s26
	s_mov_b64 s[10:11], 0

.LBB0_348:
	s_cmpk_gt_i32 s14, 0x3fff
	s_cselect_b64 s[16:17], -1, 0
	s_or_b64 s[20:21], s[72:73], s[16:17]
	s_mov_b64 s[18:19], -1
	s_and_b64 vcc, exec, s[20:21]
	s_cbranch_vccnz .LBB0_350
	s_ashr_i32 s15, s14, 31
	s_lshl_b64 s[18:19], s[14:15], 12
	v_lshl_add_u64 v[48:49], v[84:85], 0, s[18:19]
	global_load_dwordx2 v[50:51], v[48:49], off
	global_load_dwordx2 v[52:53], v[48:49], off offset:512
	global_load_dwordx2 v[54:55], v[48:49], off offset:1024
	global_load_dwordx2 v[56:57], v[48:49], off offset:1536
	s_mov_b64 s[18:19], 0
	s_mov_b32 s100, 1

.LBB0_387:
	s_cmpk_gt_i32 s2, 0x3fff
	s_cselect_b64 s[14:15], -1, 0
	s_or_b64 s[18:19], s[72:73], s[14:15]
	s_mov_b64 s[16:17], -1
	s_and_b64 vcc, exec, s[18:19]
	s_cbranch_vccnz .LBB0_389
	s_ashr_i32 s3, s2, 31
	s_lshl_b64 s[16:17], s[2:3], 12
	v_lshl_add_u64 v[16:17], v[84:85], 0, s[16:17]
	global_load_dwordx2 v[68:69], v[16:17], off
	global_load_dwordx2 v[70:71], v[16:17], off offset:512
	global_load_dwordx2 v[72:73], v[16:17], off offset:1024
	global_load_dwordx2 v[74:75], v[16:17], off offset:1536
	s_mov_b64 s[16:17], 0
	s_mov_b32 s101, 1
